# v40 plus attention main loop unrolled to six steps with static LDS ring base registers (no per-step address adds)
# speedup vs baseline: 1.0169x; 1.0060x over previous
; __device__ __forceinline__ int otid() { int t = threadIdx.x; asm volatile("" : "+v"(t)); return t; }
; #define WAIT_BAR(N) asm volatile("s_waitcnt vmcnt(" #N ") lgkmcnt(0)\n\ts_barrier":::"memory")
;   #define DMA_K(t,slot) glds16(ksrc+(long)(t)*KVBLK*KVP,(unsigned)__builtin_amdgcn_readfirstlane(kdst+(slot)))
;   #define DMA_V(t,slot) glds16(vsrc+(long)(t)*KVBLK*KVP,(unsigned)__builtin_amdgcn_readfirstlane(vdst+(slot)))
;   #define CMASK(P0,P1,t) do{}while(0)
;   #define CMASK(P0,P1,t) do{}while(0)
;   #define CMASK(P0,P1,t) do{}while(0)
; template<int THRL> __device__ __forceinline__ void attn_unit(const bf16*Qu,const bf16*__restrict__ Kh,const bf16*__restrict__ Vh,bf16*Ou,const int NT,const float shift,char*shm){
;   const int tid=otid(),lane=tid&63,r32=lane&31,hi=lane>>5; const int wid=__builtin_amdgcn_readfirstlane(tid>>6);
;   const bf16*Qw=Qu+(long)wid*QBLK*QP;
;   const unsigned lds0=(unsigned)(uintptr_t)shm;
;   float*wsf=(float*)(shm+LDS_WS)+wid*64;
;   const bf16*ksrc=Kh+(long)lane*KVP+wid*8;
;   const bf16*vsrc=Vh+(long)(16*(wid&3)+(lane>>2))*KVP+(wid>>2)*32+(lane&3)*8;
;   const unsigned kdst=lds0+LDS_K+wid*1024, vdst=lds0+LDS_V+wid*1024;
;     ...
;   const int vb0=(int)(lds0+LDS_V)+((lane>>4)&1)*32+(lane&3)*8+(4*hi+((lane&15)>>2))*64;
;   const char*Kbase=shm+LDS_K; bf16x8 kf[8];
;   const lds_cptr shm3=(lds_cptr)shm; const lds_cptr kp0=shm3+LDS_K+hi*1024+r32*16; const lds_cptr vp0=shm3+LDS_V+((lane>>4)&1)*32+(lane&3)*8+(4*hi+((lane&15)>>2))*64;
;   DMA_K(0,0);DMA_V(0,0);DMA_K(1,SLOTB);
;   bf16x8 qr[4];
;   #pragma unroll
;   for(int d0=0;d0<4;++d0)qr[d0]=*reinterpret_cast<const bf16x8*>(&Qw[(long)r32*QP+d0*16+hi*8]);
;   float mhat=0.f,l_reg=0.f;f32x16 o[2];o[0]=f32x16{};o[1]=f32x16{};f32x16 negm=f32x16{};asm volatile("":"+v"(negm));
;     ...
;   bool resc=false;
;     ...
;   f32x16 pA0,pA1,pB0,pB1;
;   int sl_prev=0,sl_cur=0,sl_next=SLOTB;
;     ...
;   DMA_K(2,2*SLOTB);
;   WAIT_BAR(3);
;   qkt(pA0,pA1,Kbase,qr,negm,r32,hi);asm volatile("s_nop 15\n\ts_nop 7":"+v"(pA0),"+v"(pA1));CMASK(pA0,pA1,0);
;   START(pA0,pA1);
;   _Pragma("unroll") for(int r=0;r<16;++r)pA1[r]=__builtin_amdgcn_exp2f(pA1[r]);
;   WAIT_BAR(0);
.LBB0_616:
	s_lshl_b32 s4, s84, 1
	s_ashr_i32 s5, s82, 2
	s_add_i32 s6, s4, s5
	v_readlane_b32 s4, v246, 62
	v_readlane_b32 s5, v246, 63
	s_lshl_b64 s[4:5], s[4:5], 11
	s_add_u32 s7, s57, s4
	s_addc_u32 s24, s58, s5
	s_lshl_b32 s4, s82, 6
	s_ashr_i32 s5, s4, 31
	s_lshl_b64 s[48:49], s[4:5], 1
	s_add_u32 s26, s7, s48
	s_addc_u32 s27, s24, s49
	s_mul_hi_i32 s7, s6, 0x208000
	s_mul_i32 s6, s6, 0x208000
	s_add_u32 s4, s59, s6
	s_addc_u32 s5, s60, s7
	v_mov_b32_e32 v42, v216
	s_add_u32 s6, s61, s6
	s_addc_u32 s7, s62, s7
	v_readfirstlane_b32 s69, v42
	s_ashr_i32 s44, s69, 6
	s_ashr_i32 s45, s44, 31
	v_and_b32_e32 v238, 63, v42
	s_lshl_b64 s[24:25], s[44:45], 16
	s_add_u32 s24, s26, s24
	v_lshlrev_b32_e32 v0, 4, v42
	s_addc_u32 s25, s27, s25
	v_lshl_add_u64 v[2:3], s[4:5], 0, v[0:1]
	s_mov_b32 s4, 0
	s_ashr_i32 s5, s4, 31
	v_lshl_add_u64 v[212:213], s[4:5], 1, v[2:3]
	s_lshl_b32 s4, s44, 4
	v_bfe_u32 v0, v42, 2, 4
	v_and_or_b32 v0, s4, 48, v0
	s_ashr_i32 s4, s69, 3
	s_andn2_b32 s4, s4, 31
	v_lshlrev_b32_e32 v0, 7, v0
	s_ashr_i32 s5, s4, 31
	s_lshl_b32 s70, s44, 10
	v_lshl_add_u64 v[2:3], s[6:7], 0, v[0:1]
	v_lshlrev_b32_e32 v239, 3, v42
	s_cmp_lg_u32 0, -1
	v_lshl_add_u64 v[2:3], s[4:5], 1, v[2:3]
	v_and_b32_e32 v242, 24, v239
	s_cselect_b32 s4, 0, 0
	v_and_b32_e32 v240, 31, v42
	v_lshlrev_b32_e32 v0, 4, v42
	s_add_i32 s70, s70, s4
	s_mov_b32 s4, m0
	s_mov_b32 m0, s70
	s_nop 0
	global_load_lds_dwordx4 v[212:213], off
	s_mov_b32 m0, s4
	v_bfe_u32 v241, v42, 5, 1
	v_lshl_add_u64 v[214:215], s[6:7], 0, v[0:1]
	s_add_i32 s71, s70, 0x6000
	s_mov_b32 s4, m0
	s_mov_b32 m0, s71
	s_nop 0
	global_load_lds_dwordx4 v[214:215], off
	s_mov_b32 m0, s4
	s_mov_b64 s[26:27], 0x2000
	v_lshlrev_b32_e32 v0, 11, v240
	v_lshl_add_u64 v[2:3], v[212:213], 0, s[26:27]
	s_add_i32 s4, s70, 0x2000
	s_mov_b32 s5, m0
	s_mov_b32 m0, s4
	s_nop 0
	global_load_lds_dwordx4 v[2:3], off
	s_mov_b32 m0, s5
	v_lshl_or_b32 v0, v241, 4, v0
	global_load_dwordx4 v[150:153], v0, s[24:25]
	global_load_dwordx4 v[138:141], v0, s[24:25] offset:32
	global_load_dwordx4 v[134:137], v0, s[24:25] offset:64
	global_load_dwordx4 v[130:133], v0, s[24:25] offset:96
	v_mov_b32_e32 v2, v1
	v_mov_b32_e32 v3, v1
	v_mov_b32_e32 v4, v1
	v_mov_b32_e32 v5, v1
	v_mov_b32_e32 v6, v1
	v_mov_b32_e32 v7, v1
	v_mov_b32_e32 v8, v1
	v_mov_b32_e32 v9, v1
	v_mov_b32_e32 v10, v1
	v_mov_b32_e32 v11, v1
	v_mov_b32_e32 v12, v1
	v_mov_b32_e32 v13, v1
	v_mov_b32_e32 v14, v1
	v_mov_b32_e32 v15, v1
	v_lshlrev_b32_e32 v0, 10, v241
	v_lshlrev_b32_e32 v16, 4, v240
	v_add3_u32 v244, 0, v0, v16
	v_mov_b32_e32 v0, v1
	v_mov_b64_e32 v[16:17], v[14:15]
	v_mov_b64_e32 v[14:15], v[12:13]
	v_mov_b64_e32 v[12:13], v[10:11]
	v_mov_b64_e32 v[10:11], v[8:9]
	v_mov_b64_e32 v[8:9], v[6:7]
	v_mov_b64_e32 v[6:7], v[4:5]
	v_mov_b64_e32 v[4:5], v[2:3]
	v_mov_b64_e32 v[2:3], v[0:1]
	v_lshl_add_u64 v[18:19], v[212:213], 0, s[72:73]
	s_add_i32 s4, s70, 0x4000
	s_mov_b32 s5, m0
	s_mov_b32 m0, s4
	s_nop 0
	global_load_lds_dwordx4 v[18:19], off
	s_mov_b32 m0, s5
	s_waitcnt vmcnt(3) lgkmcnt(0)
	s_barrier
	ds_read_b128 v[34:37], v244
	ds_read_b128 v[38:41], v244 offset:512
	v_lshlrev_b32_e32 v0, 1, v42
	v_and_b32_e32 v243, 32, v0
	s_mov_b64 s[34:35], 0x6000
	v_add_u32_e32 v50, 0, v243
	s_mov_b32 s5, 1
	s_mov_b32 s4, 0
	s_movk_i32 s31, 0x2000
	s_mov_b32 s24, 0
	s_movk_i32 s76, 0x4000
	s_waitcnt vmcnt(3) lgkmcnt(1)
	v_mfma_f32_32x32x16_bf16 v[18:33], v[34:37], v[150:153], v[2:17]
	s_waitcnt lgkmcnt(0)
	v_mfma_f32_32x32x16_bf16 v[2:17], v[38:41], v[150:153], v[2:17]
	ds_read_b128 v[34:37], v244 offset:2048
	ds_read_b128 v[38:41], v244 offset:2560
	s_waitcnt vmcnt(2) lgkmcnt(1)
	v_mfma_f32_32x32x16_bf16 v[18:33], v[34:37], v[138:141], v[18:33]
	s_waitcnt lgkmcnt(0)
	v_mfma_f32_32x32x16_bf16 v[2:17], v[38:41], v[138:141], v[2:17]
	ds_read_b128 v[34:37], v244 offset:4096
	ds_read_b128 v[38:41], v244 offset:4608
	s_waitcnt vmcnt(1) lgkmcnt(1)
	v_mfma_f32_32x32x16_bf16 v[18:33], v[34:37], v[134:137], v[18:33]
	ds_read_b128 v[34:37], v244 offset:6144
	s_waitcnt lgkmcnt(1)
	v_mfma_f32_32x32x16_bf16 v[2:17], v[38:41], v[134:137], v[2:17]
	ds_read_b128 v[38:41], v244 offset:6656
	s_waitcnt vmcnt(0) lgkmcnt(1)
	v_mfma_f32_32x32x16_bf16 v[18:33], v[34:37], v[130:133], v[18:33]
	v_add_f32_e32 v34, v1, v237
	v_lshlrev_b32_e32 v35, 4, v42
	v_xor_b32_e32 v34, 0x80000000, v34
	v_and_b32_e32 v0, 0xc0, v35
	v_mov_b32_e32 v35, v34
	v_mov_b32_e32 v36, v34
	v_mov_b32_e32 v37, v34
	s_waitcnt lgkmcnt(0)
	v_mfma_f32_32x32x16_bf16 v[2:17], v[38:41], v[130:133], v[2:17]
	s_nop 15
	s_nop 7
	v_mov_b32_e32 v38, v34
	v_mov_b32_e32 v39, v34
	v_mov_b32_e32 v40, v34
	v_mov_b32_e32 v41, v34
	v_mov_b32_e32 v42, v34
	v_mov_b32_e32 v43, v34
	v_mov_b32_e32 v44, v34
	v_mov_b32_e32 v45, v34
	v_mov_b32_e32 v46, v34
	v_mov_b32_e32 v47, v34
	v_mov_b32_e32 v48, v34
	v_mov_b32_e32 v49, v34
	v_sub_f32_e32 v2, v2, v237
	v_sub_f32_e32 v3, v3, v237
	s_waitcnt vmcnt(0) lgkmcnt(0)
	s_barrier
; #define WAIT_BAR(N) asm volatile("s_waitcnt vmcnt(" #N ") lgkmcnt(0)\n\ts_barrier":::"memory")
;   #define DMA_K(t,slot) glds16(ksrc+(long)(t)*KVBLK*KVP,(unsigned)__builtin_amdgcn_readfirstlane(kdst+(slot)))
;   #define DMA_V(t,slot) glds16(vsrc+(long)(t)*KVBLK*KVP,(unsigned)__builtin_amdgcn_readfirstlane(vdst+(slot)))
;   #define ROT() do{sl_prev=sl_cur;sl_cur=sl_next;sl_next=(sl_next==(NSLOT-1)*SLOTB)?0:sl_next+SLOTB;}while(0)
; template<int THRL> __device__ __forceinline__ void attn_unit(const bf16*Qu,const bf16*__restrict__ Kh,const bf16*__restrict__ Vh,bf16*Ou,const int NT,const float shift,char*shm){
;     ...
;   WAIT_BAR(0);
;   DMA_K(3,0);DMA_V(1,SLOTB);
;   ROT();
;   kload8(kf,kp0+sl_cur);
;   WAIT_BAR(2);
;   s16x4 vlo[8],vhi[8]; u32x4 pw0,pw1,pw2,pw3;
	v_sub_f32_e32 v18, v18, v237
	v_sub_f32_e32 v19, v19, v237
	s_nop 0
	v_exp_f32_e32 v66, v2
	v_exp_f32_e32 v67, v3
	v_lshl_add_u64 v[2:3], v[212:213], 0, s[34:35]
	s_mov_b32 s6, m0
	s_mov_b32 m0, s70
	s_nop 0
	global_load_lds_dwordx4 v[2:3], off
	s_mov_b32 m0, s6
	v_lshl_add_u64 v[2:3], v[214:215], 0, s[26:27]
	s_add_i32 s6, s70, 0x8000
	s_mov_b32 s7, m0
	s_mov_b32 m0, s6
	s_nop 0
	global_load_lds_dwordx4 v[2:3], off
	s_mov_b32 m0, s7
	ds_read_b128 v[190:193], v244 offset:8192
	ds_read_b128 v[186:189], v244 offset:8704
	ds_read_b128 v[182:185], v244 offset:10240
	ds_read_b128 v[178:181], v244 offset:10752
	ds_read_b128 v[174:177], v244 offset:12288
	ds_read_b128 v[170:173], v244 offset:12800
	ds_read_b128 v[166:169], v244 offset:14336
	ds_read_b128 v[162:165], v244 offset:14848
	v_sub_f32_e32 v20, v20, v237
	v_sub_f32_e32 v4, v4, v237
	v_sub_f32_e32 v21, v21, v237
	v_sub_f32_e32 v5, v5, v237
	v_sub_f32_e32 v22, v22, v237
	v_sub_f32_e32 v6, v6, v237
	v_sub_f32_e32 v23, v23, v237
	v_sub_f32_e32 v7, v7, v237
	v_sub_f32_e32 v24, v24, v237
	v_sub_f32_e32 v8, v8, v237
	v_sub_f32_e32 v25, v25, v237
	v_sub_f32_e32 v9, v9, v237
	v_sub_f32_e32 v26, v26, v237
	v_sub_f32_e32 v10, v10, v237
	v_sub_f32_e32 v27, v27, v237
	v_sub_f32_e32 v11, v11, v237
	v_sub_f32_e32 v28, v28, v237
	v_sub_f32_e32 v12, v12, v237
	v_sub_f32_e32 v29, v29, v237
	v_sub_f32_e32 v13, v13, v237
	v_sub_f32_e32 v30, v30, v237
	v_sub_f32_e32 v14, v14, v237
	v_sub_f32_e32 v31, v31, v237
	v_sub_f32_e32 v15, v15, v237
	v_sub_f32_e32 v32, v32, v237
	v_sub_f32_e32 v16, v16, v237
	v_sub_f32_e32 v33, v33, v237
	v_sub_f32_e32 v17, v17, v237
	v_exp_f32_e32 v82, v18
	v_exp_f32_e32 v83, v19
	v_exp_f32_e32 v84, v20
	v_exp_f32_e32 v85, v21
	v_exp_f32_e32 v86, v22
	v_exp_f32_e32 v87, v23
	v_exp_f32_e32 v88, v24
	v_exp_f32_e32 v89, v25
	v_exp_f32_e32 v90, v26
	v_exp_f32_e32 v91, v27
	v_exp_f32_e32 v92, v28
	v_exp_f32_e32 v93, v29
	v_exp_f32_e32 v94, v30
	v_exp_f32_e32 v95, v31
	v_exp_f32_e32 v96, v32
	v_exp_f32_e32 v97, v33
	v_exp_f32_e32 v68, v4
	v_exp_f32_e32 v69, v5
	v_exp_f32_e32 v70, v6
	v_exp_f32_e32 v71, v7
	v_exp_f32_e32 v72, v8
	v_exp_f32_e32 v73, v9
	v_exp_f32_e32 v74, v10
	v_exp_f32_e32 v75, v11
	v_exp_f32_e32 v76, v12
	v_exp_f32_e32 v77, v13
	v_exp_f32_e32 v78, v14
	v_exp_f32_e32 v79, v15
	v_exp_f32_e32 v80, v16
	v_exp_f32_e32 v81, v17
	s_waitcnt vmcnt(2) lgkmcnt(0)
	s_barrier
	v_lshl_or_b32 v0, v241, 8, v0
	v_add3_u32 v245, v50, v242, v0
	s_cmp_lt_i32 s91, 7
	s_cbranch_scc1 .LBB0_620
	s_mov_b64 s[4:5], 0xa000
	v_mov_b32_e32 v199, v245
	v_add_u32_e32 v200, 0x2000, v245
	v_add_u32_e32 v201, 0x4000, v245
	v_mov_b32_e32 v202, v244
	v_add_u32_e32 v203, 0x2000, v244
	v_add_u32_e32 v204, 0x4000, v244
	v_mov_b32_e32 v50, 0
	v_mov_b32_e32 v194, 0
	v_mov_b32_e32 v195, 0
	v_mov_b32_e32 v196, 0
	v_lshlrev_b32_e32 v197, 4, v238
	v_readfirstlane_b32 s98, v212
	v_readfirstlane_b32 s99, v213
	v_readfirstlane_b32 s100, v214
	v_readfirstlane_b32 s101, v215
	s_add_u32 s98, s98, 0x8000
	s_addc_u32 s99, s99, 0
	s_add_u32 s100, s100, 0x4000
	s_addc_u32 s101, s101, 0
	s_mov_b32 s26, 6
	v_mov_b32_e32 v2, 0
	v_mov_b32_e32 v3, v50
	v_mov_b32_e32 v4, v50
	v_mov_b32_e32 v5, v50
	v_mov_b32_e32 v6, v50
	v_mov_b32_e32 v7, v50
	v_mov_b32_e32 v8, v50
	v_mov_b32_e32 v9, v50
	v_mov_b32_e32 v10, v50
	v_mov_b32_e32 v11, v50
	v_mov_b32_e32 v12, v50
	v_mov_b32_e32 v13, v50
	v_mov_b32_e32 v14, v50
	v_mov_b32_e32 v15, v50
	v_mov_b32_e32 v16, v50
	v_mov_b32_e32 v17, v50
	v_mov_b32_e32 v18, 0
	v_mov_b32_e32 v19, v50
	v_mov_b32_e32 v20, v50
	v_mov_b32_e32 v21, v50
	v_mov_b32_e32 v22, v50
	v_mov_b32_e32 v23, v50
	v_mov_b32_e32 v24, v50
	v_mov_b32_e32 v25, v50
	v_mov_b32_e32 v26, v50
	v_mov_b32_e32 v27, v50
	v_mov_b32_e32 v28, v50
	v_mov_b32_e32 v29, v50
	v_mov_b32_e32 v30, v50
	v_mov_b32_e32 v31, v50
	v_mov_b32_e32 v32, v50
	v_mov_b32_e32 v33, v50
.LBB0_618:
	s_mov_b32 s4, s76
	s_mov_b32 s5, s26
	s_mov_b32 s25, s31
	ds_read_b64_tr_b16 v[52:53], v199 offset:24576
	ds_read_b64_tr_b16 v[54:55], v199 offset:25088
	s_waitcnt lgkmcnt(9)
	v_mfma_f32_32x32x16_bf16 v[114:129], v[190:193], v[150:153], v[34:49]
	v_add_f32_e32 v50, v82, v50
	v_add_f32_e32 v194, v83, v194
	v_add_f32_e32 v195, v84, v195
	v_add_f32_e32 v196, v85, v196
	v_add_f32_e32 v50, v86, v50
	v_add_f32_e32 v194, v87, v194
	v_cvt_pk_bf16_f32 v158, v82, v83
	v_cvt_pk_bf16_f32 v159, v84, v85
	ds_read_b64_tr_b16 v[60:61], v199 offset:28672
	ds_read_b64_tr_b16 v[62:63], v199 offset:29184
	s_waitcnt lgkmcnt(10)
	v_mfma_f32_32x32x16_bf16 v[98:113], v[186:189], v[150:153], v[34:49]
	v_add_f32_e32 v195, v88, v195
	v_add_f32_e32 v196, v89, v196
	v_add_f32_e32 v50, v90, v50
	v_add_f32_e32 v194, v91, v194
	v_cvt_pk_bf16_f32 v160, v86, v87
	v_cvt_pk_bf16_f32 v161, v88, v89
	ds_read_b64_tr_b16 v[82:83], v199 offset:25600
	ds_read_b64_tr_b16 v[84:85], v199 offset:26112
	s_waitcnt lgkmcnt(11)
	v_mfma_f32_32x32x16_bf16 v[114:129], v[182:185], v[138:141], v[114:129]
	v_add_f32_e32 v195, v92, v195
	v_add_f32_e32 v196, v93, v196
	v_add_f32_e32 v50, v94, v50
	v_add_f32_e32 v194, v95, v194
	v_cvt_pk_bf16_f32 v154, v90, v91
	v_cvt_pk_bf16_f32 v155, v92, v93
	ds_read_b64_tr_b16 v[86:87], v199 offset:29696
	ds_read_b64_tr_b16 v[88:89], v199 offset:30208
	s_waitcnt lgkmcnt(12)
	v_mfma_f32_32x32x16_bf16 v[98:113], v[178:181], v[138:141], v[98:113]
	v_add_f32_e32 v195, v96, v195
	v_add_f32_e32 v196, v97, v196
	v_add_f32_e32 v50, v66, v50
	v_add_f32_e32 v194, v67, v194
	v_cvt_pk_bf16_f32 v156, v94, v95
	v_cvt_pk_bf16_f32 v157, v96, v97
	ds_read_b64_tr_b16 v[90:91], v199 offset:26624
	ds_read_b64_tr_b16 v[92:93], v199 offset:27136
	s_waitcnt lgkmcnt(13)
; #define WAIT_BAR(N) asm volatile("s_waitcnt vmcnt(" #N ") lgkmcnt(0)\n\ts_barrier":::"memory")
;   #define RESC() do{ if(resc){ asm volatile("s_waitcnt lgkmcnt(0)":::"memory"); \
;       _Pragma("unroll") for(int d_=0;d_<2;++d_) _Pragma("unroll") for(int r=0;r<16;++r)o[d_][r]*=wsf[crow(r,hi)]; } }while(0)
;   #define ROT() do{sl_prev=sl_cur;sl_cur=sl_next;sl_next=(sl_next==(NSLOT-1)*SLOTB)?0:sl_next+SLOTB;}while(0)
; template<int THRL> __device__ __forceinline__ void attn_unit(const bf16*Qu,const bf16*__restrict__ Kh,const bf16*__restrict__ Vh,bf16*Ou,const int NT,const float shift,char*shm){
;     ...
;   int t=1;
;     ...
;   for(;t+5<NT;t+=2){
;     STEP(pB0,pB1,pA0,pA1,t,true,true,true);     WAIT_BAR(2); RESC(); ROT();
	v_mfma_f32_32x32x16_bf16 v[114:129], v[174:177], v[134:137], v[114:129]
	v_add_f32_e32 v195, v68, v195
	v_add_f32_e32 v196, v69, v196
	v_add_f32_e32 v50, v70, v50
	v_add_f32_e32 v194, v71, v194
	v_cvt_pk_bf16_f32 v146, v66, v67
	v_cvt_pk_bf16_f32 v147, v68, v69
	ds_read_b64_tr_b16 v[64:65], v199 offset:30720
	ds_read_b64_tr_b16 v[66:67], v199 offset:31232
	s_waitcnt lgkmcnt(14)
	v_mfma_f32_32x32x16_bf16 v[98:113], v[170:173], v[134:137], v[98:113]
	v_add_f32_e32 v195, v72, v195
	v_add_f32_e32 v196, v73, v196
	v_add_f32_e32 v50, v74, v50
	v_add_f32_e32 v194, v75, v194
	v_cvt_pk_bf16_f32 v148, v70, v71
	v_cvt_pk_bf16_f32 v149, v72, v73
	ds_read_b64_tr_b16 v[68:69], v199 offset:27648
	ds_read_b64_tr_b16 v[70:71], v199 offset:28160
	s_waitcnt lgkmcnt(14)
	v_mfma_f32_32x32x16_bf16 v[114:129], v[166:169], v[130:133], v[114:129]
	v_add_f32_e32 v195, v76, v195
	v_add_f32_e32 v196, v77, v196
	v_add_f32_e32 v50, v78, v50
	v_add_f32_e32 v194, v79, v194
	v_cvt_pk_bf16_f32 v142, v74, v75
	v_cvt_pk_bf16_f32 v143, v76, v77
	ds_read_b64_tr_b16 v[72:73], v199 offset:31744
	ds_read_b64_tr_b16 v[74:75], v199 offset:32256
	v_mfma_f32_32x32x16_bf16 v[98:113], v[162:165], v[130:133], v[98:113]
	v_add_f32_e32 v195, v80, v195
	v_add_f32_e32 v196, v81, v196
	v_cvt_pk_bf16_f32 v144, v78, v79
	v_cvt_pk_bf16_f32 v145, v80, v81
	s_add_i32 s6, s31, s70
	s_mov_b32 s7, m0
	s_mov_b32 m0, s6
	s_nop 0
	global_load_lds_dwordx4 v197, s[98:99]
	s_mov_b32 m0, s7
	s_add_i32 s6, s76, s71
	s_mov_b32 s7, m0
	s_mov_b32 m0, s6
	s_nop 0
	global_load_lds_dwordx4 v197, s[100:101]
	s_mov_b32 m0, s7
	s_add_u32 s98, s98, 0x2000
	s_addc_u32 s99, s99, 0
	s_add_u32 s100, s100, 0x2000
	s_addc_u32 s101, s101, 0
	s_waitcnt lgkmcnt(14)
	v_mfma_f32_32x32x16_bf16 v[2:17], v[158:161], v[52:55], v[2:17]
	v_exp_f32_e32 v114, v114
	v_exp_f32_e32 v115, v115
	v_exp_f32_e32 v116, v116
	v_exp_f32_e32 v117, v117
	s_waitcnt lgkmcnt(12)
	v_mfma_f32_32x32x16_bf16 v[18:33], v[158:161], v[60:63], v[18:33]
	v_exp_f32_e32 v118, v118
	v_exp_f32_e32 v119, v119
	v_exp_f32_e32 v120, v120
	v_exp_f32_e32 v121, v121
	ds_read_b128 v[60:63], v204
	ds_read_b128 v[162:165], v204 offset:512
	s_waitcnt lgkmcnt(12)
	v_mfma_f32_32x32x16_bf16 v[2:17], v[154:157], v[82:85], v[2:17]
	v_exp_f32_e32 v122, v122
	v_exp_f32_e32 v123, v123
	v_exp_f32_e32 v124, v124
	v_exp_f32_e32 v125, v125
	ds_read_b128 v[166:169], v204 offset:2048
	ds_read_b128 v[170:173], v204 offset:2560
	s_waitcnt lgkmcnt(12)
	v_mfma_f32_32x32x16_bf16 v[18:33], v[154:157], v[86:89], v[18:33]
	v_exp_f32_e32 v126, v126
	v_exp_f32_e32 v127, v127
	v_exp_f32_e32 v128, v128
	v_exp_f32_e32 v129, v129
	ds_read_b128 v[174:177], v204 offset:4096
	ds_read_b128 v[178:181], v204 offset:4608
	s_waitcnt lgkmcnt(12)
	v_mfma_f32_32x32x16_bf16 v[2:17], v[146:149], v[90:93], v[2:17]
	v_exp_f32_e32 v98, v98
	v_exp_f32_e32 v99, v99
	v_exp_f32_e32 v100, v100
	v_exp_f32_e32 v101, v101
	ds_read_b128 v[182:185], v204 offset:6144
	ds_read_b128 v[52:55], v204 offset:6656
	s_waitcnt lgkmcnt(12)
	v_mfma_f32_32x32x16_bf16 v[18:33], v[146:149], v[64:67], v[18:33]
	v_exp_f32_e32 v102, v102
	v_exp_f32_e32 v103, v103
	v_exp_f32_e32 v104, v104
	v_exp_f32_e32 v105, v105
	s_waitcnt lgkmcnt(10)
	v_mfma_f32_32x32x16_bf16 v[2:17], v[142:145], v[68:71], v[2:17]
	v_exp_f32_e32 v106, v106
	v_exp_f32_e32 v107, v107
	v_exp_f32_e32 v108, v108
	v_exp_f32_e32 v109, v109
	s_waitcnt lgkmcnt(8)
	v_mfma_f32_32x32x16_bf16 v[18:33], v[142:145], v[72:75], v[18:33]
	v_exp_f32_e32 v110, v110
	v_exp_f32_e32 v111, v111
	v_exp_f32_e32 v112, v112
	v_exp_f32_e32 v113, v113
	s_waitcnt vmcnt(2) lgkmcnt(0)
	s_barrier
	s_add_i32 s6, s76, 0x2000
	s_cmpk_lg_i32 s76, 0x4000
	s_cselect_b32 s31, s6, 0
	ds_read_b64_tr_b16 v[186:187], v200 offset:24576
	ds_read_b64_tr_b16 v[188:189], v200 offset:25088
	s_waitcnt lgkmcnt(9)
	v_mfma_f32_32x32x16_bf16 v[82:97], v[60:63], v[150:153], v[34:49]
	v_add_f32_e32 v50, v114, v50
	v_add_f32_e32 v194, v115, v194
	v_add_f32_e32 v195, v116, v195
	v_add_f32_e32 v196, v117, v196
	v_add_f32_e32 v50, v118, v50
	v_add_f32_e32 v194, v119, v194
	v_cvt_pk_bf16_f32 v158, v114, v115
	v_cvt_pk_bf16_f32 v159, v116, v117
	ds_read_b64_tr_b16 v[60:61], v200 offset:28672
	ds_read_b64_tr_b16 v[62:63], v200 offset:29184
	s_waitcnt lgkmcnt(10)
	v_mfma_f32_32x32x16_bf16 v[66:81], v[162:165], v[150:153], v[34:49]
	v_add_f32_e32 v195, v120, v195
	v_add_f32_e32 v196, v121, v196
	v_add_f32_e32 v50, v122, v50
	v_add_f32_e32 v194, v123, v194
	v_cvt_pk_bf16_f32 v160, v118, v119
	v_cvt_pk_bf16_f32 v161, v120, v121
	ds_read_b64_tr_b16 v[114:115], v200 offset:25600
	ds_read_b64_tr_b16 v[116:117], v200 offset:26112
	s_waitcnt lgkmcnt(11)
	v_mfma_f32_32x32x16_bf16 v[82:97], v[166:169], v[138:141], v[82:97]
	v_add_f32_e32 v195, v124, v195
	v_add_f32_e32 v196, v125, v196
	v_add_f32_e32 v50, v126, v50
	v_add_f32_e32 v194, v127, v194
	v_cvt_pk_bf16_f32 v154, v122, v123
	v_cvt_pk_bf16_f32 v155, v124, v125
	ds_read_b64_tr_b16 v[118:119], v200 offset:29696
	ds_read_b64_tr_b16 v[120:121], v200 offset:30208
	s_waitcnt lgkmcnt(12)
	v_mfma_f32_32x32x16_bf16 v[66:81], v[170:173], v[138:141], v[66:81]
	v_add_f32_e32 v195, v128, v195
	v_add_f32_e32 v196, v129, v196
	v_add_f32_e32 v50, v98, v50
	v_add_f32_e32 v194, v99, v194
	v_cvt_pk_bf16_f32 v156, v126, v127
	v_cvt_pk_bf16_f32 v157, v128, v129
	ds_read_b64_tr_b16 v[122:123], v200 offset:26624
	ds_read_b64_tr_b16 v[124:125], v200 offset:27136
	s_waitcnt lgkmcnt(13)
	v_mfma_f32_32x32x16_bf16 v[82:97], v[174:177], v[134:137], v[82:97]
	v_add_f32_e32 v195, v100, v195
	v_add_f32_e32 v196, v101, v196
	v_add_f32_e32 v50, v102, v50
	v_add_f32_e32 v194, v103, v194
	v_cvt_pk_bf16_f32 v146, v98, v99
	v_cvt_pk_bf16_f32 v147, v100, v101
	ds_read_b64_tr_b16 v[98:99], v200 offset:30720
	ds_read_b64_tr_b16 v[100:101], v200 offset:31232
	s_waitcnt lgkmcnt(14)
; #define WAIT_BAR(N) asm volatile("s_waitcnt vmcnt(" #N ") lgkmcnt(0)\n\ts_barrier":::"memory")
;   #define RESC() do{ if(resc){ asm volatile("s_waitcnt lgkmcnt(0)":::"memory"); \
;       _Pragma("unroll") for(int d_=0;d_<2;++d_) _Pragma("unroll") for(int r=0;r<16;++r)o[d_][r]*=wsf[crow(r,hi)]; } }while(0)
;   #define ROT() do{sl_prev=sl_cur;sl_cur=sl_next;sl_next=(sl_next==(NSLOT-1)*SLOTB)?0:sl_next+SLOTB;}while(0)
; template<int THRL> __device__ __forceinline__ void attn_unit(const bf16*Qu,const bf16*__restrict__ Kh,const bf16*__restrict__ Vh,bf16*Ou,const int NT,const float shift,char*shm){
;     ...
;   int t=1;
;     ...
;   for(;t+5<NT;t+=2){
;     STEP(pB0,pB1,pA0,pA1,t,true,true,true);     WAIT_BAR(2); RESC(); ROT();
;     STEP(pA0,pA1,pB0,pB1,t+1,true,true,true);   WAIT_BAR(2); RESC(); ROT();
;   }
	v_mfma_f32_32x32x16_bf16 v[66:81], v[178:181], v[134:137], v[66:81]
	v_add_f32_e32 v195, v104, v195
	v_add_f32_e32 v196, v105, v196
	v_add_f32_e32 v50, v106, v50
	v_add_f32_e32 v194, v107, v194
	v_cvt_pk_bf16_f32 v148, v102, v103
	v_cvt_pk_bf16_f32 v149, v104, v105
	ds_read_b64_tr_b16 v[102:103], v200 offset:27648
	ds_read_b64_tr_b16 v[104:105], v200 offset:28160
	s_waitcnt lgkmcnt(14)
	v_mfma_f32_32x32x16_bf16 v[82:97], v[182:185], v[130:133], v[82:97]
	v_add_f32_e32 v195, v108, v195
	v_add_f32_e32 v196, v109, v196
	v_add_f32_e32 v50, v110, v50
	v_add_f32_e32 v194, v111, v194
	v_cvt_pk_bf16_f32 v142, v106, v107
	v_cvt_pk_bf16_f32 v143, v108, v109
	ds_read_b64_tr_b16 v[106:107], v200 offset:31744
	ds_read_b64_tr_b16 v[108:109], v200 offset:32256
	v_mfma_f32_32x32x16_bf16 v[66:81], v[52:55], v[130:133], v[66:81]
	v_add_f32_e32 v195, v112, v195
	v_add_f32_e32 v196, v113, v196
	v_cvt_pk_bf16_f32 v144, v110, v111
	v_cvt_pk_bf16_f32 v145, v112, v113
	s_add_i32 s6, s76, s70
	s_mov_b32 s7, m0
	s_mov_b32 m0, s6
	s_nop 0
	global_load_lds_dwordx4 v197, s[98:99]
	s_mov_b32 m0, s7
	s_add_i32 s6, s31, s71
	s_mov_b32 s7, m0
	s_mov_b32 m0, s6
	s_nop 0
	global_load_lds_dwordx4 v197, s[100:101]
	s_mov_b32 m0, s7
	s_add_u32 s98, s98, 0x2000
	s_addc_u32 s99, s99, 0
	s_add_u32 s100, s100, 0x2000
	s_addc_u32 s101, s101, 0
	s_waitcnt lgkmcnt(14)
	v_mfma_f32_32x32x16_bf16 v[2:17], v[158:161], v[186:189], v[2:17]
	v_exp_f32_e32 v82, v82
	v_exp_f32_e32 v83, v83
	v_exp_f32_e32 v84, v84
	v_exp_f32_e32 v85, v85
	s_waitcnt lgkmcnt(12)
	v_mfma_f32_32x32x16_bf16 v[18:33], v[158:161], v[60:63], v[18:33]
	v_exp_f32_e32 v86, v86
	v_exp_f32_e32 v87, v87
	v_exp_f32_e32 v88, v88
	v_exp_f32_e32 v89, v89
	ds_read_b128 v[190:193], v202
	ds_read_b128 v[186:189], v202 offset:512
	s_waitcnt lgkmcnt(12)
	v_mfma_f32_32x32x16_bf16 v[2:17], v[154:157], v[114:117], v[2:17]
	v_exp_f32_e32 v90, v90
	v_exp_f32_e32 v91, v91
	v_exp_f32_e32 v92, v92
	v_exp_f32_e32 v93, v93
	ds_read_b128 v[182:185], v202 offset:2048
	ds_read_b128 v[178:181], v202 offset:2560
	s_waitcnt lgkmcnt(12)
	v_mfma_f32_32x32x16_bf16 v[18:33], v[154:157], v[118:121], v[18:33]
	v_exp_f32_e32 v94, v94
	v_exp_f32_e32 v95, v95
	v_exp_f32_e32 v96, v96
	v_exp_f32_e32 v97, v97
	ds_read_b128 v[174:177], v202 offset:4096
	ds_read_b128 v[170:173], v202 offset:4608
	s_waitcnt lgkmcnt(12)
	v_mfma_f32_32x32x16_bf16 v[2:17], v[146:149], v[122:125], v[2:17]
	v_exp_f32_e32 v66, v66
	v_exp_f32_e32 v67, v67
	v_exp_f32_e32 v68, v68
	v_exp_f32_e32 v69, v69
	ds_read_b128 v[166:169], v202 offset:6144
	ds_read_b128 v[162:165], v202 offset:6656
	s_waitcnt lgkmcnt(12)
	v_mfma_f32_32x32x16_bf16 v[18:33], v[146:149], v[98:101], v[18:33]
	v_exp_f32_e32 v70, v70
	v_exp_f32_e32 v71, v71
	v_exp_f32_e32 v72, v72
	v_exp_f32_e32 v73, v73
	s_waitcnt lgkmcnt(10)
	v_mfma_f32_32x32x16_bf16 v[2:17], v[142:145], v[102:105], v[2:17]
	v_exp_f32_e32 v74, v74
	v_exp_f32_e32 v75, v75
	v_exp_f32_e32 v76, v76
	v_exp_f32_e32 v77, v77
	s_waitcnt lgkmcnt(8)
	v_mfma_f32_32x32x16_bf16 v[18:33], v[142:145], v[106:109], v[18:33]
	v_exp_f32_e32 v78, v78
	v_exp_f32_e32 v79, v79
	v_exp_f32_e32 v80, v80
	v_exp_f32_e32 v81, v81
	s_add_i32 s6, s31, 0x2000
	s_waitcnt vmcnt(2) lgkmcnt(0)
	s_barrier
	s_cmpk_lg_i32 s31, 0x4000
	s_mov_b32 s24, s76
	s_cselect_b32 s76, s6, 0
	s_add_i32 s26, s26, 2
	s_cmp_ge_i32 s26, s91
	s_cbranch_scc1 .Lattn_exit
.Lattn_cpB:
	s_mov_b32 s4, s76
	s_mov_b32 s5, s26
	s_mov_b32 s25, s31
	ds_read_b64_tr_b16 v[52:53], v201 offset:24576
	ds_read_b64_tr_b16 v[54:55], v201 offset:25088
	s_waitcnt lgkmcnt(9)
	v_mfma_f32_32x32x16_bf16 v[114:129], v[190:193], v[150:153], v[34:49]
	v_add_f32_e32 v50, v82, v50
	v_add_f32_e32 v194, v83, v194
	v_add_f32_e32 v195, v84, v195
	v_add_f32_e32 v196, v85, v196
	v_add_f32_e32 v50, v86, v50
	v_add_f32_e32 v194, v87, v194
	v_cvt_pk_bf16_f32 v158, v82, v83
	v_cvt_pk_bf16_f32 v159, v84, v85
	ds_read_b64_tr_b16 v[60:61], v201 offset:28672
	ds_read_b64_tr_b16 v[62:63], v201 offset:29184
	s_waitcnt lgkmcnt(10)
	v_mfma_f32_32x32x16_bf16 v[98:113], v[186:189], v[150:153], v[34:49]
	v_add_f32_e32 v195, v88, v195
	v_add_f32_e32 v196, v89, v196
	v_add_f32_e32 v50, v90, v50
	v_add_f32_e32 v194, v91, v194
	v_cvt_pk_bf16_f32 v160, v86, v87
	v_cvt_pk_bf16_f32 v161, v88, v89
	ds_read_b64_tr_b16 v[82:83], v201 offset:25600
	ds_read_b64_tr_b16 v[84:85], v201 offset:26112
	s_waitcnt lgkmcnt(11)
	v_mfma_f32_32x32x16_bf16 v[114:129], v[182:185], v[138:141], v[114:129]
	v_add_f32_e32 v195, v92, v195
	v_add_f32_e32 v196, v93, v196
	v_add_f32_e32 v50, v94, v50
	v_add_f32_e32 v194, v95, v194
	v_cvt_pk_bf16_f32 v154, v90, v91
	v_cvt_pk_bf16_f32 v155, v92, v93
	ds_read_b64_tr_b16 v[86:87], v201 offset:29696
	ds_read_b64_tr_b16 v[88:89], v201 offset:30208
	s_waitcnt lgkmcnt(12)
	v_mfma_f32_32x32x16_bf16 v[98:113], v[178:181], v[138:141], v[98:113]
	v_add_f32_e32 v195, v96, v195
	v_add_f32_e32 v196, v97, v196
	v_add_f32_e32 v50, v66, v50
	v_add_f32_e32 v194, v67, v194
	v_cvt_pk_bf16_f32 v156, v94, v95
	v_cvt_pk_bf16_f32 v157, v96, v97
	ds_read_b64_tr_b16 v[90:91], v201 offset:26624
	ds_read_b64_tr_b16 v[92:93], v201 offset:27136
	s_waitcnt lgkmcnt(13)
	v_mfma_f32_32x32x16_bf16 v[114:129], v[174:177], v[134:137], v[114:129]
	v_add_f32_e32 v195, v68, v195
	v_add_f32_e32 v196, v69, v196
	v_add_f32_e32 v50, v70, v50
	v_add_f32_e32 v194, v71, v194
	v_cvt_pk_bf16_f32 v146, v66, v67
	v_cvt_pk_bf16_f32 v147, v68, v69
	ds_read_b64_tr_b16 v[64:65], v201 offset:30720
	ds_read_b64_tr_b16 v[66:67], v201 offset:31232
	s_waitcnt lgkmcnt(14)
; #define WAIT_BAR(N) asm volatile("s_waitcnt vmcnt(" #N ") lgkmcnt(0)\n\ts_barrier":::"memory")
;   #define RESC() do{ if(resc){ asm volatile("s_waitcnt lgkmcnt(0)":::"memory"); \
;       _Pragma("unroll") for(int d_=0;d_<2;++d_) _Pragma("unroll") for(int r=0;r<16;++r)o[d_][r]*=wsf[crow(r,hi)]; } }while(0)
;   #define ROT() do{sl_prev=sl_cur;sl_cur=sl_next;sl_next=(sl_next==(NSLOT-1)*SLOTB)?0:sl_next+SLOTB;}while(0)
; template<int THRL> __device__ __forceinline__ void attn_unit(const bf16*Qu,const bf16*__restrict__ Kh,const bf16*__restrict__ Vh,bf16*Ou,const int NT,const float shift,char*shm){
;     ...
;   int t=1;
;     ...
;   for(;t+5<NT;t+=2){
;     STEP(pB0,pB1,pA0,pA1,t,true,true,true);     WAIT_BAR(2); RESC(); ROT();
;     STEP(pA0,pA1,pB0,pB1,t+1,true,true,true);   WAIT_BAR(2); RESC(); ROT();
;   }
	v_mfma_f32_32x32x16_bf16 v[98:113], v[170:173], v[134:137], v[98:113]
	v_add_f32_e32 v195, v72, v195
	v_add_f32_e32 v196, v73, v196
	v_add_f32_e32 v50, v74, v50
	v_add_f32_e32 v194, v75, v194
	v_cvt_pk_bf16_f32 v148, v70, v71
	v_cvt_pk_bf16_f32 v149, v72, v73
	ds_read_b64_tr_b16 v[68:69], v201 offset:27648
	ds_read_b64_tr_b16 v[70:71], v201 offset:28160
	s_waitcnt lgkmcnt(14)
	v_mfma_f32_32x32x16_bf16 v[114:129], v[166:169], v[130:133], v[114:129]
	v_add_f32_e32 v195, v76, v195
	v_add_f32_e32 v196, v77, v196
	v_add_f32_e32 v50, v78, v50
	v_add_f32_e32 v194, v79, v194
	v_cvt_pk_bf16_f32 v142, v74, v75
	v_cvt_pk_bf16_f32 v143, v76, v77
	ds_read_b64_tr_b16 v[72:73], v201 offset:31744
	ds_read_b64_tr_b16 v[74:75], v201 offset:32256
	v_mfma_f32_32x32x16_bf16 v[98:113], v[162:165], v[130:133], v[98:113]
	v_add_f32_e32 v195, v80, v195
	v_add_f32_e32 v196, v81, v196
	v_cvt_pk_bf16_f32 v144, v78, v79
	v_cvt_pk_bf16_f32 v145, v80, v81
	s_add_i32 s6, s31, s70
	s_mov_b32 s7, m0
	s_mov_b32 m0, s6
	s_nop 0
	global_load_lds_dwordx4 v197, s[98:99]
	s_mov_b32 m0, s7
	s_add_i32 s6, s76, s71
	s_mov_b32 s7, m0
	s_mov_b32 m0, s6
	s_nop 0
	global_load_lds_dwordx4 v197, s[100:101]
	s_mov_b32 m0, s7
	s_add_u32 s98, s98, 0x2000
	s_addc_u32 s99, s99, 0
	s_add_u32 s100, s100, 0x2000
	s_addc_u32 s101, s101, 0
	s_waitcnt lgkmcnt(14)
	v_mfma_f32_32x32x16_bf16 v[2:17], v[158:161], v[52:55], v[2:17]
	v_exp_f32_e32 v114, v114
	v_exp_f32_e32 v115, v115
	v_exp_f32_e32 v116, v116
	v_exp_f32_e32 v117, v117
	s_waitcnt lgkmcnt(12)
	v_mfma_f32_32x32x16_bf16 v[18:33], v[158:161], v[60:63], v[18:33]
	v_exp_f32_e32 v118, v118
	v_exp_f32_e32 v119, v119
	v_exp_f32_e32 v120, v120
	v_exp_f32_e32 v121, v121
	ds_read_b128 v[60:63], v203
	ds_read_b128 v[162:165], v203 offset:512
	s_waitcnt lgkmcnt(12)
	v_mfma_f32_32x32x16_bf16 v[2:17], v[154:157], v[82:85], v[2:17]
	v_exp_f32_e32 v122, v122
	v_exp_f32_e32 v123, v123
	v_exp_f32_e32 v124, v124
	v_exp_f32_e32 v125, v125
	ds_read_b128 v[166:169], v203 offset:2048
	ds_read_b128 v[170:173], v203 offset:2560
	s_waitcnt lgkmcnt(12)
	v_mfma_f32_32x32x16_bf16 v[18:33], v[154:157], v[86:89], v[18:33]
	v_exp_f32_e32 v126, v126
	v_exp_f32_e32 v127, v127
	v_exp_f32_e32 v128, v128
	v_exp_f32_e32 v129, v129
	ds_read_b128 v[174:177], v203 offset:4096
	ds_read_b128 v[178:181], v203 offset:4608
	s_waitcnt lgkmcnt(12)
	v_mfma_f32_32x32x16_bf16 v[2:17], v[146:149], v[90:93], v[2:17]
	v_exp_f32_e32 v98, v98
	v_exp_f32_e32 v99, v99
	v_exp_f32_e32 v100, v100
	v_exp_f32_e32 v101, v101
	ds_read_b128 v[182:185], v203 offset:6144
	ds_read_b128 v[52:55], v203 offset:6656
	s_waitcnt lgkmcnt(12)
	v_mfma_f32_32x32x16_bf16 v[18:33], v[146:149], v[64:67], v[18:33]
	v_exp_f32_e32 v102, v102
	v_exp_f32_e32 v103, v103
	v_exp_f32_e32 v104, v104
	v_exp_f32_e32 v105, v105
	s_waitcnt lgkmcnt(10)
	v_mfma_f32_32x32x16_bf16 v[2:17], v[142:145], v[68:71], v[2:17]
	v_exp_f32_e32 v106, v106
	v_exp_f32_e32 v107, v107
	v_exp_f32_e32 v108, v108
	v_exp_f32_e32 v109, v109
	s_waitcnt lgkmcnt(8)
	v_mfma_f32_32x32x16_bf16 v[18:33], v[142:145], v[72:75], v[18:33]
	v_exp_f32_e32 v110, v110
	v_exp_f32_e32 v111, v111
	v_exp_f32_e32 v112, v112
	v_exp_f32_e32 v113, v113
	s_waitcnt vmcnt(2) lgkmcnt(0)
	s_barrier
	s_add_i32 s6, s76, 0x2000
	s_cmpk_lg_i32 s76, 0x4000
	s_cselect_b32 s31, s6, 0
	ds_read_b64_tr_b16 v[186:187], v199 offset:24576
	ds_read_b64_tr_b16 v[188:189], v199 offset:25088
	s_waitcnt lgkmcnt(9)
	v_mfma_f32_32x32x16_bf16 v[82:97], v[60:63], v[150:153], v[34:49]
	v_add_f32_e32 v50, v114, v50
	v_add_f32_e32 v194, v115, v194
	v_add_f32_e32 v195, v116, v195
	v_add_f32_e32 v196, v117, v196
	v_add_f32_e32 v50, v118, v50
	v_add_f32_e32 v194, v119, v194
	v_cvt_pk_bf16_f32 v158, v114, v115
	v_cvt_pk_bf16_f32 v159, v116, v117
	ds_read_b64_tr_b16 v[60:61], v199 offset:28672
	ds_read_b64_tr_b16 v[62:63], v199 offset:29184
	s_waitcnt lgkmcnt(10)
	v_mfma_f32_32x32x16_bf16 v[66:81], v[162:165], v[150:153], v[34:49]
	v_add_f32_e32 v195, v120, v195
	v_add_f32_e32 v196, v121, v196
	v_add_f32_e32 v50, v122, v50
	v_add_f32_e32 v194, v123, v194
	v_cvt_pk_bf16_f32 v160, v118, v119
	v_cvt_pk_bf16_f32 v161, v120, v121
	ds_read_b64_tr_b16 v[114:115], v199 offset:25600
	ds_read_b64_tr_b16 v[116:117], v199 offset:26112
	s_waitcnt lgkmcnt(11)
	v_mfma_f32_32x32x16_bf16 v[82:97], v[166:169], v[138:141], v[82:97]
	v_add_f32_e32 v195, v124, v195
	v_add_f32_e32 v196, v125, v196
	v_add_f32_e32 v50, v126, v50
	v_add_f32_e32 v194, v127, v194
	v_cvt_pk_bf16_f32 v154, v122, v123
	v_cvt_pk_bf16_f32 v155, v124, v125
	ds_read_b64_tr_b16 v[118:119], v199 offset:29696
	ds_read_b64_tr_b16 v[120:121], v199 offset:30208
	s_waitcnt lgkmcnt(12)
	v_mfma_f32_32x32x16_bf16 v[66:81], v[170:173], v[138:141], v[66:81]
	v_add_f32_e32 v195, v128, v195
	v_add_f32_e32 v196, v129, v196
	v_add_f32_e32 v50, v98, v50
	v_add_f32_e32 v194, v99, v194
	v_cvt_pk_bf16_f32 v156, v126, v127
	v_cvt_pk_bf16_f32 v157, v128, v129
	ds_read_b64_tr_b16 v[122:123], v199 offset:26624
	ds_read_b64_tr_b16 v[124:125], v199 offset:27136
	s_waitcnt lgkmcnt(13)
	v_mfma_f32_32x32x16_bf16 v[82:97], v[174:177], v[134:137], v[82:97]
	v_add_f32_e32 v195, v100, v195
	v_add_f32_e32 v196, v101, v196
	v_add_f32_e32 v50, v102, v50
	v_add_f32_e32 v194, v103, v194
	v_cvt_pk_bf16_f32 v146, v98, v99
	v_cvt_pk_bf16_f32 v147, v100, v101
	ds_read_b64_tr_b16 v[98:99], v199 offset:30720
	ds_read_b64_tr_b16 v[100:101], v199 offset:31232
	s_waitcnt lgkmcnt(14)
	v_mfma_f32_32x32x16_bf16 v[66:81], v[178:181], v[134:137], v[66:81]
	v_add_f32_e32 v195, v104, v195
	v_add_f32_e32 v196, v105, v196
	v_add_f32_e32 v50, v106, v50
	v_add_f32_e32 v194, v107, v194
	v_cvt_pk_bf16_f32 v148, v102, v103
	v_cvt_pk_bf16_f32 v149, v104, v105
	ds_read_b64_tr_b16 v[102:103], v199 offset:27648
	ds_read_b64_tr_b16 v[104:105], v199 offset:28160
	s_waitcnt lgkmcnt(14)
; #define WAIT_BAR(N) asm volatile("s_waitcnt vmcnt(" #N ") lgkmcnt(0)\n\ts_barrier":::"memory")
;   #define RESC() do{ if(resc){ asm volatile("s_waitcnt lgkmcnt(0)":::"memory"); \
;       _Pragma("unroll") for(int d_=0;d_<2;++d_) _Pragma("unroll") for(int r=0;r<16;++r)o[d_][r]*=wsf[crow(r,hi)]; } }while(0)
;   #define ROT() do{sl_prev=sl_cur;sl_cur=sl_next;sl_next=(sl_next==(NSLOT-1)*SLOTB)?0:sl_next+SLOTB;}while(0)
; template<int THRL> __device__ __forceinline__ void attn_unit(const bf16*Qu,const bf16*__restrict__ Kh,const bf16*__restrict__ Vh,bf16*Ou,const int NT,const float shift,char*shm){
;     ...
;   int t=1;
;     ...
;   for(;t+5<NT;t+=2){
;     STEP(pB0,pB1,pA0,pA1,t,true,true,true);     WAIT_BAR(2); RESC(); ROT();
;     STEP(pA0,pA1,pB0,pB1,t+1,true,true,true);   WAIT_BAR(2); RESC(); ROT();
;   }
	v_mfma_f32_32x32x16_bf16 v[82:97], v[182:185], v[130:133], v[82:97]
	v_add_f32_e32 v195, v108, v195
	v_add_f32_e32 v196, v109, v196
	v_add_f32_e32 v50, v110, v50
	v_add_f32_e32 v194, v111, v194
	v_cvt_pk_bf16_f32 v142, v106, v107
	v_cvt_pk_bf16_f32 v143, v108, v109
	ds_read_b64_tr_b16 v[106:107], v199 offset:31744
	ds_read_b64_tr_b16 v[108:109], v199 offset:32256
	v_mfma_f32_32x32x16_bf16 v[66:81], v[52:55], v[130:133], v[66:81]
	v_add_f32_e32 v195, v112, v195
	v_add_f32_e32 v196, v113, v196
	v_cvt_pk_bf16_f32 v144, v110, v111
	v_cvt_pk_bf16_f32 v145, v112, v113
	s_add_i32 s6, s76, s70
	s_mov_b32 s7, m0
	s_mov_b32 m0, s6
	s_nop 0
	global_load_lds_dwordx4 v197, s[98:99]
	s_mov_b32 m0, s7
	s_add_i32 s6, s31, s71
	s_mov_b32 s7, m0
	s_mov_b32 m0, s6
	s_nop 0
	global_load_lds_dwordx4 v197, s[100:101]
	s_mov_b32 m0, s7
	s_add_u32 s98, s98, 0x2000
	s_addc_u32 s99, s99, 0
	s_add_u32 s100, s100, 0x2000
	s_addc_u32 s101, s101, 0
	s_waitcnt lgkmcnt(14)
	v_mfma_f32_32x32x16_bf16 v[2:17], v[158:161], v[186:189], v[2:17]
	v_exp_f32_e32 v82, v82
	v_exp_f32_e32 v83, v83
	v_exp_f32_e32 v84, v84
	v_exp_f32_e32 v85, v85
	s_waitcnt lgkmcnt(12)
	v_mfma_f32_32x32x16_bf16 v[18:33], v[158:161], v[60:63], v[18:33]
	v_exp_f32_e32 v86, v86
	v_exp_f32_e32 v87, v87
	v_exp_f32_e32 v88, v88
	v_exp_f32_e32 v89, v89
	ds_read_b128 v[190:193], v204
	ds_read_b128 v[186:189], v204 offset:512
	s_waitcnt lgkmcnt(12)
	v_mfma_f32_32x32x16_bf16 v[2:17], v[154:157], v[114:117], v[2:17]
	v_exp_f32_e32 v90, v90
	v_exp_f32_e32 v91, v91
	v_exp_f32_e32 v92, v92
	v_exp_f32_e32 v93, v93
	ds_read_b128 v[182:185], v204 offset:2048
	ds_read_b128 v[178:181], v204 offset:2560
	s_waitcnt lgkmcnt(12)
	v_mfma_f32_32x32x16_bf16 v[18:33], v[154:157], v[118:121], v[18:33]
	v_exp_f32_e32 v94, v94
	v_exp_f32_e32 v95, v95
	v_exp_f32_e32 v96, v96
	v_exp_f32_e32 v97, v97
	ds_read_b128 v[174:177], v204 offset:4096
	ds_read_b128 v[170:173], v204 offset:4608
	s_waitcnt lgkmcnt(12)
	v_mfma_f32_32x32x16_bf16 v[2:17], v[146:149], v[122:125], v[2:17]
	v_exp_f32_e32 v66, v66
	v_exp_f32_e32 v67, v67
	v_exp_f32_e32 v68, v68
	v_exp_f32_e32 v69, v69
	ds_read_b128 v[166:169], v204 offset:6144
	ds_read_b128 v[162:165], v204 offset:6656
	s_waitcnt lgkmcnt(12)
	v_mfma_f32_32x32x16_bf16 v[18:33], v[146:149], v[98:101], v[18:33]
	v_exp_f32_e32 v70, v70
	v_exp_f32_e32 v71, v71
	v_exp_f32_e32 v72, v72
	v_exp_f32_e32 v73, v73
	s_waitcnt lgkmcnt(10)
	v_mfma_f32_32x32x16_bf16 v[2:17], v[142:145], v[102:105], v[2:17]
	v_exp_f32_e32 v74, v74
	v_exp_f32_e32 v75, v75
	v_exp_f32_e32 v76, v76
	v_exp_f32_e32 v77, v77
	s_waitcnt lgkmcnt(8)
	v_mfma_f32_32x32x16_bf16 v[18:33], v[142:145], v[106:109], v[18:33]
	v_exp_f32_e32 v78, v78
	v_exp_f32_e32 v79, v79
	v_exp_f32_e32 v80, v80
	v_exp_f32_e32 v81, v81
	s_add_i32 s6, s31, 0x2000
	s_waitcnt vmcnt(2) lgkmcnt(0)
	s_barrier
	s_cmpk_lg_i32 s31, 0x4000
	s_mov_b32 s24, s76
	s_cselect_b32 s76, s6, 0
	s_add_i32 s26, s26, 2
	s_cmp_ge_i32 s26, s91
	s_cbranch_scc1 .Lattn_exit
.Lattn_cpC:
	s_mov_b32 s4, s76
	s_mov_b32 s5, s26
	s_mov_b32 s25, s31
	ds_read_b64_tr_b16 v[52:53], v200 offset:24576
	ds_read_b64_tr_b16 v[54:55], v200 offset:25088
	s_waitcnt lgkmcnt(9)
	v_mfma_f32_32x32x16_bf16 v[114:129], v[190:193], v[150:153], v[34:49]
	v_add_f32_e32 v50, v82, v50
	v_add_f32_e32 v194, v83, v194
	v_add_f32_e32 v195, v84, v195
	v_add_f32_e32 v196, v85, v196
	v_add_f32_e32 v50, v86, v50
	v_add_f32_e32 v194, v87, v194
	v_cvt_pk_bf16_f32 v158, v82, v83
	v_cvt_pk_bf16_f32 v159, v84, v85
	ds_read_b64_tr_b16 v[60:61], v200 offset:28672
	ds_read_b64_tr_b16 v[62:63], v200 offset:29184
	s_waitcnt lgkmcnt(10)
	v_mfma_f32_32x32x16_bf16 v[98:113], v[186:189], v[150:153], v[34:49]
	v_add_f32_e32 v195, v88, v195
	v_add_f32_e32 v196, v89, v196
	v_add_f32_e32 v50, v90, v50
	v_add_f32_e32 v194, v91, v194
	v_cvt_pk_bf16_f32 v160, v86, v87
	v_cvt_pk_bf16_f32 v161, v88, v89
	ds_read_b64_tr_b16 v[82:83], v200 offset:25600
	ds_read_b64_tr_b16 v[84:85], v200 offset:26112
	s_waitcnt lgkmcnt(11)
	v_mfma_f32_32x32x16_bf16 v[114:129], v[182:185], v[138:141], v[114:129]
	v_add_f32_e32 v195, v92, v195
	v_add_f32_e32 v196, v93, v196
	v_add_f32_e32 v50, v94, v50
	v_add_f32_e32 v194, v95, v194
	v_cvt_pk_bf16_f32 v154, v90, v91
	v_cvt_pk_bf16_f32 v155, v92, v93
	ds_read_b64_tr_b16 v[86:87], v200 offset:29696
	ds_read_b64_tr_b16 v[88:89], v200 offset:30208
	s_waitcnt lgkmcnt(12)
	v_mfma_f32_32x32x16_bf16 v[98:113], v[178:181], v[138:141], v[98:113]
	v_add_f32_e32 v195, v96, v195
	v_add_f32_e32 v196, v97, v196
	v_add_f32_e32 v50, v66, v50
	v_add_f32_e32 v194, v67, v194
	v_cvt_pk_bf16_f32 v156, v94, v95
	v_cvt_pk_bf16_f32 v157, v96, v97
	ds_read_b64_tr_b16 v[90:91], v200 offset:26624
	ds_read_b64_tr_b16 v[92:93], v200 offset:27136
	s_waitcnt lgkmcnt(13)
	v_mfma_f32_32x32x16_bf16 v[114:129], v[174:177], v[134:137], v[114:129]
	v_add_f32_e32 v195, v68, v195
	v_add_f32_e32 v196, v69, v196
	v_add_f32_e32 v50, v70, v50
	v_add_f32_e32 v194, v71, v194
	v_cvt_pk_bf16_f32 v146, v66, v67
	v_cvt_pk_bf16_f32 v147, v68, v69
	ds_read_b64_tr_b16 v[64:65], v200 offset:30720
	ds_read_b64_tr_b16 v[66:67], v200 offset:31232
	s_waitcnt lgkmcnt(14)
	v_mfma_f32_32x32x16_bf16 v[98:113], v[170:173], v[134:137], v[98:113]
	v_add_f32_e32 v195, v72, v195
	v_add_f32_e32 v196, v73, v196
	v_add_f32_e32 v50, v74, v50
	v_add_f32_e32 v194, v75, v194
	v_cvt_pk_bf16_f32 v148, v70, v71
	v_cvt_pk_bf16_f32 v149, v72, v73
	ds_read_b64_tr_b16 v[68:69], v200 offset:27648
	ds_read_b64_tr_b16 v[70:71], v200 offset:28160
	s_waitcnt lgkmcnt(14)
; #define WAIT_BAR(N) asm volatile("s_waitcnt vmcnt(" #N ") lgkmcnt(0)\n\ts_barrier":::"memory")
;   #define RESC() do{ if(resc){ asm volatile("s_waitcnt lgkmcnt(0)":::"memory"); \
;       _Pragma("unroll") for(int d_=0;d_<2;++d_) _Pragma("unroll") for(int r=0;r<16;++r)o[d_][r]*=wsf[crow(r,hi)]; } }while(0)
;   #define ROT() do{sl_prev=sl_cur;sl_cur=sl_next;sl_next=(sl_next==(NSLOT-1)*SLOTB)?0:sl_next+SLOTB;}while(0)
; template<int THRL> __device__ __forceinline__ void attn_unit(const bf16*Qu,const bf16*__restrict__ Kh,const bf16*__restrict__ Vh,bf16*Ou,const int NT,const float shift,char*shm){
;     ...
;   int t=1;
;     ...
;   for(;t+5<NT;t+=2){
;     STEP(pB0,pB1,pA0,pA1,t,true,true,true);     WAIT_BAR(2); RESC(); ROT();
;     STEP(pA0,pA1,pB0,pB1,t+1,true,true,true);   WAIT_BAR(2); RESC(); ROT();
	v_mfma_f32_32x32x16_bf16 v[114:129], v[166:169], v[130:133], v[114:129]
	v_add_f32_e32 v195, v76, v195
	v_add_f32_e32 v196, v77, v196
	v_add_f32_e32 v50, v78, v50
	v_add_f32_e32 v194, v79, v194
	v_cvt_pk_bf16_f32 v142, v74, v75
	v_cvt_pk_bf16_f32 v143, v76, v77
	ds_read_b64_tr_b16 v[72:73], v200 offset:31744
	ds_read_b64_tr_b16 v[74:75], v200 offset:32256
	v_mfma_f32_32x32x16_bf16 v[98:113], v[162:165], v[130:133], v[98:113]
	v_add_f32_e32 v195, v80, v195
	v_add_f32_e32 v196, v81, v196
	v_cvt_pk_bf16_f32 v144, v78, v79
	v_cvt_pk_bf16_f32 v145, v80, v81
	s_add_i32 s6, s31, s70
	s_mov_b32 s7, m0
	s_mov_b32 m0, s6
	s_nop 0
	global_load_lds_dwordx4 v197, s[98:99]
	s_mov_b32 m0, s7
	s_add_i32 s6, s76, s71
	s_mov_b32 s7, m0
	s_mov_b32 m0, s6
	s_nop 0
	global_load_lds_dwordx4 v197, s[100:101]
	s_mov_b32 m0, s7
	s_add_u32 s98, s98, 0x2000
	s_addc_u32 s99, s99, 0
	s_add_u32 s100, s100, 0x2000
	s_addc_u32 s101, s101, 0
	s_waitcnt lgkmcnt(14)
	v_mfma_f32_32x32x16_bf16 v[2:17], v[158:161], v[52:55], v[2:17]
	v_exp_f32_e32 v114, v114
	v_exp_f32_e32 v115, v115
	v_exp_f32_e32 v116, v116
	v_exp_f32_e32 v117, v117
	s_waitcnt lgkmcnt(12)
	v_mfma_f32_32x32x16_bf16 v[18:33], v[158:161], v[60:63], v[18:33]
	v_exp_f32_e32 v118, v118
	v_exp_f32_e32 v119, v119
	v_exp_f32_e32 v120, v120
	v_exp_f32_e32 v121, v121
	ds_read_b128 v[60:63], v202
	ds_read_b128 v[162:165], v202 offset:512
	s_waitcnt lgkmcnt(12)
	v_mfma_f32_32x32x16_bf16 v[2:17], v[154:157], v[82:85], v[2:17]
	v_exp_f32_e32 v122, v122
	v_exp_f32_e32 v123, v123
	v_exp_f32_e32 v124, v124
	v_exp_f32_e32 v125, v125
	ds_read_b128 v[166:169], v202 offset:2048
	ds_read_b128 v[170:173], v202 offset:2560
	s_waitcnt lgkmcnt(12)
	v_mfma_f32_32x32x16_bf16 v[18:33], v[154:157], v[86:89], v[18:33]
	v_exp_f32_e32 v126, v126
	v_exp_f32_e32 v127, v127
	v_exp_f32_e32 v128, v128
	v_exp_f32_e32 v129, v129
	ds_read_b128 v[174:177], v202 offset:4096
	ds_read_b128 v[178:181], v202 offset:4608
	s_waitcnt lgkmcnt(12)
	v_mfma_f32_32x32x16_bf16 v[2:17], v[146:149], v[90:93], v[2:17]
	v_exp_f32_e32 v98, v98
	v_exp_f32_e32 v99, v99
	v_exp_f32_e32 v100, v100
	v_exp_f32_e32 v101, v101
	ds_read_b128 v[182:185], v202 offset:6144
	ds_read_b128 v[52:55], v202 offset:6656
	s_waitcnt lgkmcnt(12)
	v_mfma_f32_32x32x16_bf16 v[18:33], v[146:149], v[64:67], v[18:33]
	v_exp_f32_e32 v102, v102
	v_exp_f32_e32 v103, v103
	v_exp_f32_e32 v104, v104
	v_exp_f32_e32 v105, v105
	s_waitcnt lgkmcnt(10)
	v_mfma_f32_32x32x16_bf16 v[2:17], v[142:145], v[68:71], v[2:17]
	v_exp_f32_e32 v106, v106
	v_exp_f32_e32 v107, v107
	v_exp_f32_e32 v108, v108
	v_exp_f32_e32 v109, v109
	s_waitcnt lgkmcnt(8)
	v_mfma_f32_32x32x16_bf16 v[18:33], v[142:145], v[72:75], v[18:33]
	v_exp_f32_e32 v110, v110
	v_exp_f32_e32 v111, v111
	v_exp_f32_e32 v112, v112
	v_exp_f32_e32 v113, v113
	s_waitcnt vmcnt(2) lgkmcnt(0)
	s_barrier
; #define WAIT_BAR(N) asm volatile("s_waitcnt vmcnt(" #N ") lgkmcnt(0)\n\ts_barrier":::"memory")
;   #define RESC() do{ if(resc){ asm volatile("s_waitcnt lgkmcnt(0)":::"memory"); \
;       _Pragma("unroll") for(int d_=0;d_<2;++d_) _Pragma("unroll") for(int r=0;r<16;++r)o[d_][r]*=wsf[crow(r,hi)]; } }while(0)
;   #define ROT() do{sl_prev=sl_cur;sl_cur=sl_next;sl_next=(sl_next==(NSLOT-1)*SLOTB)?0:sl_next+SLOTB;}while(0)
; template<int THRL> __device__ __forceinline__ void attn_unit(const bf16*Qu,const bf16*__restrict__ Kh,const bf16*__restrict__ Vh,bf16*Ou,const int NT,const float shift,char*shm){
;     ...
;   int t=1;
;     ...
;   for(;t+5<NT;t+=2){
;     STEP(pB0,pB1,pA0,pA1,t,true,true,true);     WAIT_BAR(2); RESC(); ROT();
;     STEP(pA0,pA1,pB0,pB1,t+1,true,true,true);   WAIT_BAR(2); RESC(); ROT();
;   }
	s_add_i32 s6, s76, 0x2000
	s_cmpk_lg_i32 s76, 0x4000
	s_cselect_b32 s31, s6, 0
	ds_read_b64_tr_b16 v[186:187], v201 offset:24576
	ds_read_b64_tr_b16 v[188:189], v201 offset:25088
	s_waitcnt lgkmcnt(9)
	v_mfma_f32_32x32x16_bf16 v[82:97], v[60:63], v[150:153], v[34:49]
	v_add_f32_e32 v50, v114, v50
	v_add_f32_e32 v194, v115, v194
	v_add_f32_e32 v195, v116, v195
	v_add_f32_e32 v196, v117, v196
	v_add_f32_e32 v50, v118, v50
	v_add_f32_e32 v194, v119, v194
	v_cvt_pk_bf16_f32 v158, v114, v115
	v_cvt_pk_bf16_f32 v159, v116, v117
	ds_read_b64_tr_b16 v[60:61], v201 offset:28672
	ds_read_b64_tr_b16 v[62:63], v201 offset:29184
	s_waitcnt lgkmcnt(10)
	v_mfma_f32_32x32x16_bf16 v[66:81], v[162:165], v[150:153], v[34:49]
	v_add_f32_e32 v195, v120, v195
	v_add_f32_e32 v196, v121, v196
	v_add_f32_e32 v50, v122, v50
	v_add_f32_e32 v194, v123, v194
	v_cvt_pk_bf16_f32 v160, v118, v119
	v_cvt_pk_bf16_f32 v161, v120, v121
	ds_read_b64_tr_b16 v[114:115], v201 offset:25600
	ds_read_b64_tr_b16 v[116:117], v201 offset:26112
	s_waitcnt lgkmcnt(11)
	v_mfma_f32_32x32x16_bf16 v[82:97], v[166:169], v[138:141], v[82:97]
	v_add_f32_e32 v195, v124, v195
	v_add_f32_e32 v196, v125, v196
	v_add_f32_e32 v50, v126, v50
	v_add_f32_e32 v194, v127, v194
	v_cvt_pk_bf16_f32 v154, v122, v123
	v_cvt_pk_bf16_f32 v155, v124, v125
	ds_read_b64_tr_b16 v[118:119], v201 offset:29696
	ds_read_b64_tr_b16 v[120:121], v201 offset:30208
	s_waitcnt lgkmcnt(12)
	v_mfma_f32_32x32x16_bf16 v[66:81], v[170:173], v[138:141], v[66:81]
	v_add_f32_e32 v195, v128, v195
	v_add_f32_e32 v196, v129, v196
	v_add_f32_e32 v50, v98, v50
	v_add_f32_e32 v194, v99, v194
	v_cvt_pk_bf16_f32 v156, v126, v127
	v_cvt_pk_bf16_f32 v157, v128, v129
	ds_read_b64_tr_b16 v[122:123], v201 offset:26624
	ds_read_b64_tr_b16 v[124:125], v201 offset:27136
	s_waitcnt lgkmcnt(13)
	v_mfma_f32_32x32x16_bf16 v[82:97], v[174:177], v[134:137], v[82:97]
	v_add_f32_e32 v195, v100, v195
	v_add_f32_e32 v196, v101, v196
	v_add_f32_e32 v50, v102, v50
	v_add_f32_e32 v194, v103, v194
	v_cvt_pk_bf16_f32 v146, v98, v99
	v_cvt_pk_bf16_f32 v147, v100, v101
	ds_read_b64_tr_b16 v[98:99], v201 offset:30720
	ds_read_b64_tr_b16 v[100:101], v201 offset:31232
	s_waitcnt lgkmcnt(14)
	v_mfma_f32_32x32x16_bf16 v[66:81], v[178:181], v[134:137], v[66:81]
	v_add_f32_e32 v195, v104, v195
	v_add_f32_e32 v196, v105, v196
	v_add_f32_e32 v50, v106, v50
	v_add_f32_e32 v194, v107, v194
	v_cvt_pk_bf16_f32 v148, v102, v103
	v_cvt_pk_bf16_f32 v149, v104, v105
	ds_read_b64_tr_b16 v[102:103], v201 offset:27648
	ds_read_b64_tr_b16 v[104:105], v201 offset:28160
	s_waitcnt lgkmcnt(14)
	v_mfma_f32_32x32x16_bf16 v[82:97], v[182:185], v[130:133], v[82:97]
	v_add_f32_e32 v195, v108, v195
	v_add_f32_e32 v196, v109, v196
	v_add_f32_e32 v50, v110, v50
	v_add_f32_e32 v194, v111, v194
	v_cvt_pk_bf16_f32 v142, v106, v107
	v_cvt_pk_bf16_f32 v143, v108, v109
	ds_read_b64_tr_b16 v[106:107], v201 offset:31744
	ds_read_b64_tr_b16 v[108:109], v201 offset:32256
	v_mfma_f32_32x32x16_bf16 v[66:81], v[52:55], v[130:133], v[66:81]
	v_add_f32_e32 v195, v112, v195
	v_add_f32_e32 v196, v113, v196
	v_cvt_pk_bf16_f32 v144, v110, v111
	v_cvt_pk_bf16_f32 v145, v112, v113
	s_add_i32 s6, s76, s70
	s_mov_b32 s7, m0
	s_mov_b32 m0, s6
	s_nop 0
	global_load_lds_dwordx4 v197, s[98:99]
	s_mov_b32 m0, s7
	s_add_i32 s6, s31, s71
	s_mov_b32 s7, m0
	s_mov_b32 m0, s6
	s_nop 0
	global_load_lds_dwordx4 v197, s[100:101]
	s_mov_b32 m0, s7
	s_add_u32 s98, s98, 0x2000
	s_addc_u32 s99, s99, 0
	s_add_u32 s100, s100, 0x2000
	s_addc_u32 s101, s101, 0
	s_waitcnt lgkmcnt(14)
	v_mfma_f32_32x32x16_bf16 v[2:17], v[158:161], v[186:189], v[2:17]
	v_exp_f32_e32 v82, v82
	v_exp_f32_e32 v83, v83
	v_exp_f32_e32 v84, v84
	v_exp_f32_e32 v85, v85
	s_waitcnt lgkmcnt(12)
	v_mfma_f32_32x32x16_bf16 v[18:33], v[158:161], v[60:63], v[18:33]
	v_exp_f32_e32 v86, v86
	v_exp_f32_e32 v87, v87
	v_exp_f32_e32 v88, v88
	v_exp_f32_e32 v89, v89
	ds_read_b128 v[190:193], v203
	ds_read_b128 v[186:189], v203 offset:512
	s_waitcnt lgkmcnt(12)
	v_mfma_f32_32x32x16_bf16 v[2:17], v[154:157], v[114:117], v[2:17]
	v_exp_f32_e32 v90, v90
	v_exp_f32_e32 v91, v91
	v_exp_f32_e32 v92, v92
	v_exp_f32_e32 v93, v93
	ds_read_b128 v[182:185], v203 offset:2048
	ds_read_b128 v[178:181], v203 offset:2560
	s_waitcnt lgkmcnt(12)
	v_mfma_f32_32x32x16_bf16 v[18:33], v[154:157], v[118:121], v[18:33]
	v_exp_f32_e32 v94, v94
	v_exp_f32_e32 v95, v95
	v_exp_f32_e32 v96, v96
	v_exp_f32_e32 v97, v97
	ds_read_b128 v[174:177], v203 offset:4096
	ds_read_b128 v[170:173], v203 offset:4608
	s_waitcnt lgkmcnt(12)
	v_mfma_f32_32x32x16_bf16 v[2:17], v[146:149], v[122:125], v[2:17]
	v_exp_f32_e32 v66, v66
	v_exp_f32_e32 v67, v67
	v_exp_f32_e32 v68, v68
	v_exp_f32_e32 v69, v69
	ds_read_b128 v[166:169], v203 offset:6144
	ds_read_b128 v[162:165], v203 offset:6656
	s_waitcnt lgkmcnt(12)
	v_mfma_f32_32x32x16_bf16 v[18:33], v[146:149], v[98:101], v[18:33]
	v_exp_f32_e32 v70, v70
	v_exp_f32_e32 v71, v71
	v_exp_f32_e32 v72, v72
	v_exp_f32_e32 v73, v73
	s_waitcnt lgkmcnt(10)
	v_mfma_f32_32x32x16_bf16 v[2:17], v[142:145], v[102:105], v[2:17]
	v_exp_f32_e32 v74, v74
	v_exp_f32_e32 v75, v75
	v_exp_f32_e32 v76, v76
	v_exp_f32_e32 v77, v77
	s_waitcnt lgkmcnt(8)
	v_mfma_f32_32x32x16_bf16 v[18:33], v[142:145], v[106:109], v[18:33]
	v_exp_f32_e32 v78, v78
	v_exp_f32_e32 v79, v79
	v_exp_f32_e32 v80, v80
	v_exp_f32_e32 v81, v81
	s_add_i32 s6, s31, 0x2000
	s_waitcnt vmcnt(2) lgkmcnt(0)
	s_barrier
	s_cmpk_lg_i32 s31, 0x4000
	s_mov_b32 s24, s76
	s_cselect_b32 s76, s6, 0
	s_add_i32 s26, s26, 2
	s_cmp_ge_i32 s26, s91
	s_cbranch_scc0 .LBB0_618
.Lattn_exit:
	v_add_f32_e32 v50, v50, v194
	v_add_f32_e32 v50, v50, v195
	v_add_f32_e32 v50, v50, v196
	s_add_i32 s5, s5, -3
	s_branch .LBB0_621
